# mLSTM scan normaliser: max(|den|, fl) without the two canonicalising maxes; den broadcast as DPP on the max (12 fewer VALU per step)
# speedup vs baseline: 1.0007x; 1.0007x over previous
; template <bool GDN, int NT> __device__ __forceinline__ void scan_load(const Frame& F, int b, int h, int dir, const ScanLane& L, int s, ScanOps<NT>& o) {
;     ...
;         const char* zq = upin((const char*)F.Z + ((size_t)chunk_row0(b, cidx) * ZW + ZC_LQ + h * 64) * 2);
; #pragma unroll
;         for (int ks = 0; ks < 2; ++ks) { o.Qf[ks] = ldu<bf16x8>(zq + ks * 64, L.zq); o.Mf[ks] = o.Qf[ks]; }
;         const char* base = (const char*)F.PM + (size_t)ud * 20480;
;         const char* bO = upin(base); const char* bB = upin(base + 10240);
; #pragma unroll
;         for (int pr = 0; pr < 2; ++pr) { const v4u qb = ldun<v4u>(bB + pr * 1024, L.o16p), qo = ldun<v4u>(bO + pr * 1024, L.o16p);
;             o.bv[2 * pr] = (v2u){qb.x, qb.y}; o.bv[2 * pr + 1] = (v2u){qb.z, qb.w}; o.ov[2 * pr] = (v2u){qo.x, qo.y}; o.ov[2 * pr + 1] = (v2u){qo.z, qo.w}; }
;         o.bv[4] = ldun<v2u>(bB + 2048, L.o8); o.ov[4] = ldun<v2u>(bO + 2048, L.o8);
;         o.wi = ldu<f32x4>(upin((const char*)F.WI + (size_t)ud * 256), L.wi);
;     ...
;     const float gl = ((const LAS float*)(St + 4 * 80 * 72))[(dir ? (s < 4 ? 3 - s : 39 - s) : s) * 2 + dir];
;     f32x4 O[NT];
; #pragma unroll
;     for (int t = 0; t < NT; ++t) {
;         const LAS bf16_t* sp2 = Sb + (16 * t + lr) * 72 + 8 * lq;
;         const bf16x8 s0 = *(const LAS bf16x8*)sp2, s1 = *(const LAS bf16x8*)(sp2 + 32);
;         const f32x4 bv = unpack4(use.bv[t]), ov = unpack4(use.ov[t]);
;         if (GDN) {
;             f32x4 o = ov, sn = S[t] * gl + bv;
;             o = __builtin_amdgcn_mfma_f32_16x16x32_bf16(use.Qf[0], s0, o, 0, 0, 0); o = __builtin_amdgcn_mfma_f32_16x16x32_bf16(use.Qf[1], s1, o, 0, 0, 0);
;             sn = __builtin_amdgcn_mfma_f32_16x16x32_bf16(use.Mf[0], s0, sn, 0, 0, 0); sn = __builtin_amdgcn_mfma_f32_16x16x32_bf16(use.Mf[1], s1, sn, 0, 0, 0);
;             S[t] = sn; O[t] = o;
;         } else {
;             f32x4 o = {0.f, 0.f, 0.f, 0.f};
;             o = __builtin_amdgcn_mfma_f32_16x16x32_bf16(use.Qf[0], s0, o, 0, 0, 0); o = __builtin_amdgcn_mfma_f32_16x16x32_bf16(use.Qf[1], s1, o, 0, 0, 0);
;             S[t] = S[t] * gl + bv; O[t] = o * use.wi + ov; }
;     }
;     if (!GDN) {
; #pragma unroll
;         for (int i = 0; i < 4; ++i) { const float den = row16_bcast<0>(O[NT - 1][i]), fl = row16_bcast<1>(O[NT - 1][i]); const float dv = frcp(fmaxf(fabsf(den), fl));
; #pragma unroll
.LBB0_346:
	s_add_i32 s0, s25, 5
	s_min_u32 s3, s0, 33
	s_add_i32 s6, s3, 2
	s_sub_i32 s3, 37, s3
	s_and_b64 s[4:5], s[90:91], exec
	s_cselect_b32 s3, s6, s3
	s_lshl_b32 s4, s3, 6
	s_add_i32 s4, s4, s33
	s_add_i32 s3, s3, s31
	s_mulk_i32 s4, 0xd00
	s_lshl_b32 s3, s3, 1
	s_or_b32 s4, s36, s4
	s_mov_b32 s5, s37
	s_add_i32 s92, s3, s68
	s_lshl_b64 s[4:5], s[4:5], 1
	s_add_u32 s4, s16, s4
	s_addc_u32 s5, s17, s5
	global_load_dwordx4 v[24:27], v28, s[4:5]
	global_load_dwordx4 v[20:23], v28, s[4:5] offset:64
	s_mul_i32 s4, s92, 0x5000
	v_readlane_b32 s5, v254, 46
	s_mul_hi_u32 s3, s92, 0x5000
	s_add_u32 s4, s5, s4
	v_readlane_b32 s5, v254, 47
	s_addc_u32 s5, s5, s3
	s_mov_b64 s[6:7], s[4:5]
	s_add_u32 s4, s4, 0x2800
	s_addc_u32 s5, s5, 0
	s_nop 0
	global_load_dwordx4 v[44:47], v32, s[4:5] nt
	global_load_dwordx4 v[28:31], v32, s[4:5] offset:1024 nt
	global_load_dwordx4 v[52:55], v32, s[6:7] nt
	s_nop 0
	global_load_dwordx4 v[32:35], v32, s[6:7] offset:1024 nt
	s_nop 0
	global_load_dwordx2 v[140:141], v100, s[4:5] offset:2048 nt
	global_load_dwordx2 v[138:139], v100, s[6:7] offset:2048 nt
	s_lshl_b64 s[4:5], s[92:93], 8
	v_readlane_b32 s6, v254, 52
	v_readlane_b32 s7, v254, 53
	s_add_u32 s4, s6, s4
	s_addc_u32 s5, s7, s5
	s_add_i32 s3, s24, 37
	v_lshl_add_u64 v[184:185], s[4:5], 0, v[0:1]
	s_and_b64 s[4:5], s[90:91], exec
	s_cselect_b32 s0, s0, s3
	s_lshl_b32 s0, s0, 3
	s_add_i32 s0, s34, s0
	v_mov_b32_e32 v0, s0
	ds_read_b32 v0, v0 offset:46080
	ds_read_b128 v[100:103], v203 offset:11520
	ds_read_b128 v[104:107], v203 offset:11584
	ds_read_b128 v[212:215], v203 offset:13824
	ds_read_b128 v[216:219], v203 offset:13888
	ds_read_b128 v[224:227], v203 offset:16128
	ds_read_b128 v[242:245], v203 offset:16192
	s_waitcnt lgkmcnt(5)
	v_mfma_f32_16x16x32_bf16 v[100:103], v[56:59], v[100:103], 0
	v_lshlrev_b32_e32 v108, 16, v84
	v_and_b32_e32 v109, 0xffff0000, v84
	v_lshlrev_b32_e32 v110, 16, v85
	s_waitcnt lgkmcnt(4)
	v_mfma_f32_16x16x32_bf16 v[100:103], v[48:51], v[104:107], v[100:103]
	v_and_b32_e32 v111, 0xffff0000, v85
	v_lshlrev_b32_e32 v112, 16, v88
	v_and_b32_e32 v113, 0xffff0000, v88
	v_lshlrev_b32_e32 v114, 16, v89
	v_and_b32_e32 v115, 0xffff0000, v89
	v_pk_fma_f32 v[150:151], v[192:193], v[0:1], v[110:111] op_sel_hi:[1,0,1]
	v_pk_fma_f32 v[148:149], v[190:191], v[0:1], v[108:109] op_sel_hi:[1,0,1]
	v_pk_fma_f32 v[108:109], v[74:75], v[102:103], v[114:115]
	v_pk_fma_f32 v[110:111], v[72:73], v[100:101], v[112:113]
	s_waitcnt lgkmcnt(3)
	v_mfma_f32_16x16x32_bf16 v[100:103], v[56:59], v[212:215], 0
	v_lshlrev_b32_e32 v112, 16, v86
	v_and_b32_e32 v113, 0xffff0000, v86
	v_lshlrev_b32_e32 v114, 16, v87
	s_waitcnt lgkmcnt(2)
	v_mfma_f32_16x16x32_bf16 v[100:103], v[48:51], v[216:219], v[100:103]
	ds_read_b128 v[212:215], v203 offset:18432
	ds_read_b128 v[216:219], v203 offset:18496
	v_and_b32_e32 v115, 0xffff0000, v87
	v_lshlrev_b32_e32 v116, 16, v90
	v_and_b32_e32 v117, 0xffff0000, v90
	v_lshlrev_b32_e32 v118, 16, v91
	v_and_b32_e32 v119, 0xffff0000, v91
	v_pk_fma_f32 v[152:153], v[188:189], v[0:1], v[114:115] op_sel_hi:[1,0,1]
	v_pk_fma_f32 v[154:155], v[154:155], v[0:1], v[112:113] op_sel_hi:[1,0,1]
	s_nop 0
	v_pk_fma_f32 v[112:113], v[74:75], v[102:103], v[118:119]
	v_pk_fma_f32 v[114:115], v[72:73], v[100:101], v[116:117]
	s_waitcnt lgkmcnt(3)
	v_mfma_f32_16x16x32_bf16 v[100:103], v[56:59], v[224:227], 0
	v_lshlrev_b32_e32 v116, 16, v76
	v_and_b32_e32 v117, 0xffff0000, v76
	v_lshlrev_b32_e32 v118, 16, v77
	s_waitcnt lgkmcnt(2)
	v_mfma_f32_16x16x32_bf16 v[100:103], v[48:51], v[242:245], v[100:103]
	ds_read_b128 v[224:227], v203 offset:20736
	ds_read_b128 v[242:245], v203 offset:20800
	v_and_b32_e32 v119, 0xffff0000, v77
	v_lshlrev_b32_e32 v160, 16, v80
	v_and_b32_e32 v161, 0xffff0000, v80
	v_lshlrev_b32_e32 v166, 16, v81
	v_and_b32_e32 v167, 0xffff0000, v81
	v_pk_fma_f32 v[156:157], v[186:187], v[0:1], v[118:119] op_sel_hi:[1,0,1]
	v_pk_fma_f32 v[158:159], v[182:183], v[0:1], v[116:117] op_sel_hi:[1,0,1]
	s_nop 0
	v_pk_fma_f32 v[116:117], v[74:75], v[102:103], v[166:167]
	v_pk_fma_f32 v[118:119], v[72:73], v[100:101], v[160:161]
	s_waitcnt lgkmcnt(3)
	v_mfma_f32_16x16x32_bf16 v[100:103], v[56:59], v[212:215], 0
	v_lshlrev_b32_e32 v166, 16, v78
	v_and_b32_e32 v167, 0xffff0000, v78
	v_lshlrev_b32_e32 v160, 16, v79
	s_waitcnt lgkmcnt(2)
	v_mfma_f32_16x16x32_bf16 v[100:103], v[48:51], v[216:219], v[100:103]
	v_and_b32_e32 v161, 0xffff0000, v79
	v_lshlrev_b32_e32 v168, 16, v82
	v_and_b32_e32 v169, 0xffff0000, v82
	v_lshlrev_b32_e32 v170, 16, v83
	v_and_b32_e32 v171, 0xffff0000, v83
	v_pk_fma_f32 v[160:161], v[162:163], v[0:1], v[160:161] op_sel_hi:[1,0,1]
	v_pk_fma_f32 v[162:163], v[178:179], v[0:1], v[166:167] op_sel_hi:[1,0,1]
	s_nop 0
	v_pk_fma_f32 v[166:167], v[74:75], v[102:103], v[170:171]
	v_pk_fma_f32 v[168:169], v[72:73], v[100:101], v[168:169]
	s_waitcnt lgkmcnt(1)
	v_mfma_f32_16x16x32_bf16 v[100:103], v[56:59], v[224:227], 0
	v_lshlrev_b32_e32 v174, 16, v2
	v_and_b32_e32 v175, 0xffff0000, v2
	v_lshlrev_b32_e32 v176, 16, v3
	s_waitcnt lgkmcnt(0)
	v_mfma_f32_16x16x32_bf16 v[100:103], v[48:51], v[242:245], v[100:103]
	v_and_b32_e32 v177, 0xffff0000, v3
	v_lshlrev_b32_e32 v170, 16, v144
	v_and_b32_e32 v171, 0xffff0000, v144
	v_lshlrev_b32_e32 v172, 16, v145
	v_and_b32_e32 v173, 0xffff0000, v145
	s_nop 2
	v_pk_fma_f32 v[100:101], v[72:73], v[100:101], v[174:175]
	v_pk_fma_f32 v[102:103], v[74:75], v[102:103], v[176:177]
	v_pk_fma_f32 v[178:179], v[164:165], v[0:1], v[172:173] op_sel_hi:[1,0,1]
	v_mov_b32_dpp v104, v100 row_newbcast:1 row_mask:0xf bank_mask:0xf bound_ctrl:1
	v_max_f32_dpp v100, |v100|, v104 row_newbcast:0 row_mask:0xf bank_mask:0xf bound_ctrl:1
	v_rcp_f32_e32 v100, v100
	v_mov_b32_dpp v104, v101 row_newbcast:1 row_mask:0xf bank_mask:0xf bound_ctrl:1
	v_max_f32_dpp v101, |v101|, v104 row_newbcast:0 row_mask:0xf bank_mask:0xf bound_ctrl:1
	v_rcp_f32_e32 v101, v101
	v_mov_b32_dpp v104, v102 row_newbcast:1 row_mask:0xf bank_mask:0xf bound_ctrl:1
	v_max_f32_dpp v102, |v102|, v104 row_newbcast:0 row_mask:0xf bank_mask:0xf bound_ctrl:1
	v_rcp_f32_e32 v102, v102
	v_mov_b32_dpp v104, v103 row_newbcast:1 row_mask:0xf bank_mask:0xf bound_ctrl:1
	v_max_f32_dpp v103, |v103|, v104 row_newbcast:0 row_mask:0xf bank_mask:0xf bound_ctrl:1
	v_rcp_f32_e32 v103, v103
	v_pk_fma_f32 v[164:165], v[180:181], v[0:1], v[170:171] op_sel_hi:[1,0,1]
	v_pk_mul_f32 v[104:105], v[110:111], v[100:101]
	s_add_i32 s3, s24, -6
	v_pk_mul_f32 v[106:107], v[108:109], v[102:103]
	v_pk_mul_f32 v[108:109], v[114:115], v[100:101]
	v_pk_mul_f32 v[110:111], v[112:113], v[102:103]
	v_pk_mul_f32 v[112:113], v[118:119], v[100:101]
	v_pk_mul_f32 v[114:115], v[116:117], v[102:103]
	v_pk_mul_f32 v[116:117], v[168:169], v[100:101]
	v_pk_mul_f32 v[118:119], v[166:167], v[102:103]
	s_mov_b64 s[20:21], 0
	v_mov_b32_e32 v183, v179
	v_mov_b32_e32 v182, v178
	v_mov_b32_e32 v181, v165
	v_mov_b32_e32 v180, v164

; template <bool GDN, int NT> __device__ __forceinline__ void scan_load(const Frame& F, int b, int h, int dir, const ScanLane& L, int s, ScanOps<NT>& o) {
;     ...
;         const char* zq = upin((const char*)F.Z + ((size_t)chunk_row0(b, cidx) * ZW + ZC_LQ + h * 64) * 2);
; #pragma unroll
;         for (int ks = 0; ks < 2; ++ks) { o.Qf[ks] = ldu<bf16x8>(zq + ks * 64, L.zq); o.Mf[ks] = o.Qf[ks]; }
;         const char* base = (const char*)F.PM + (size_t)ud * 20480;
;         const char* bO = upin(base); const char* bB = upin(base + 10240);
; #pragma unroll
;         for (int pr = 0; pr < 2; ++pr) { const v4u qb = ldun<v4u>(bB + pr * 1024, L.o16p), qo = ldun<v4u>(bO + pr * 1024, L.o16p);
;             o.bv[2 * pr] = (v2u){qb.x, qb.y}; o.bv[2 * pr + 1] = (v2u){qb.z, qb.w}; o.ov[2 * pr] = (v2u){qo.x, qo.y}; o.ov[2 * pr + 1] = (v2u){qo.z, qo.w}; }
;         o.bv[4] = ldun<v2u>(bB + 2048, L.o8); o.ov[4] = ldun<v2u>(bO + 2048, L.o8);
;         o.wi = ldu<f32x4>(upin((const char*)F.WI + (size_t)ud * 256), L.wi);
;     ...
;     const float gl = ((const LAS float*)(St + 4 * 80 * 72))[(dir ? (s < 4 ? 3 - s : 39 - s) : s) * 2 + dir];
;     f32x4 O[NT];
; #pragma unroll
;     for (int t = 0; t < NT; ++t) {
;         const LAS bf16_t* sp2 = Sb + (16 * t + lr) * 72 + 8 * lq;
;         const bf16x8 s0 = *(const LAS bf16x8*)sp2, s1 = *(const LAS bf16x8*)(sp2 + 32);
;         const f32x4 bv = unpack4(use.bv[t]), ov = unpack4(use.ov[t]);
;         if (GDN) {
;             f32x4 o = ov, sn = S[t] * gl + bv;
;             o = __builtin_amdgcn_mfma_f32_16x16x32_bf16(use.Qf[0], s0, o, 0, 0, 0); o = __builtin_amdgcn_mfma_f32_16x16x32_bf16(use.Qf[1], s1, o, 0, 0, 0);
;             sn = __builtin_amdgcn_mfma_f32_16x16x32_bf16(use.Mf[0], s0, sn, 0, 0, 0); sn = __builtin_amdgcn_mfma_f32_16x16x32_bf16(use.Mf[1], s1, sn, 0, 0, 0);
;             S[t] = sn; O[t] = o;
;         } else {
;             f32x4 o = {0.f, 0.f, 0.f, 0.f};
;             o = __builtin_amdgcn_mfma_f32_16x16x32_bf16(use.Qf[0], s0, o, 0, 0, 0); o = __builtin_amdgcn_mfma_f32_16x16x32_bf16(use.Qf[1], s1, o, 0, 0, 0);
;             S[t] = S[t] * gl + bv; O[t] = o * use.wi + ov; }
;     }
;     if (!GDN) {
; #pragma unroll
;         for (int i = 0; i < 4; ++i) { const float den = row16_bcast<0>(O[NT - 1][i]), fl = row16_bcast<1>(O[NT - 1][i]); const float dv = frcp(fmaxf(fabsf(den), fl));
; #pragma unroll
.LBB0_361:
	s_min_u32 s1, s25, 33
	s_add_i32 s1, s1, 2
	s_and_b64 s[4:5], exec, s[10:11]
	s_cselect_b32 s3, 3, 39
	s_sub_i32 s3, s3, s1
	s_and_b64 s[4:5], s[90:91], exec
	s_cselect_b32 s1, s1, s3
	s_lshl_b32 s3, s1, 6
	s_cmp_lt_i32 s1, 4
	s_cselect_b32 s4, s63, s33
	s_add_i32 s3, s4, s3
	s_mul_i32 s6, s3, 0xd00
	s_add_i32 s1, s1, s31
	s_ashr_i32 s7, s6, 31
	s_lshl_b32 s1, s1, 1
	s_or_b64 s[6:7], s[36:37], s[6:7]
	s_add_i32 s4, s1, s68
	s_lshl_b64 s[6:7], s[6:7], 1
	s_add_u32 s6, s16, s6
	s_addc_u32 s7, s17, s7
	global_load_dwordx4 v[56:59], v186, s[6:7]
	global_load_dwordx4 v[48:51], v186, s[6:7] offset:64
	s_ashr_i32 s5, s4, 31
	s_mul_i32 s3, s4, 0x5000
	v_readlane_b32 s6, v254, 46
	s_mul_hi_i32 s1, s4, 0x5000
	s_add_u32 s6, s6, s3
	v_readlane_b32 s3, v254, 47
	s_addc_u32 s7, s3, s1
	s_mov_b64 s[8:9], s[6:7]
	s_add_u32 s6, s6, 0x2800
	s_addc_u32 s7, s7, 0
	global_load_dwordx4 v[84:87], v185, s[6:7] nt
	global_load_dwordx4 v[88:91], v185, s[8:9] nt
	global_load_dwordx4 v[76:79], v185, s[6:7] offset:1024 nt
	global_load_dwordx4 v[80:83], v185, s[8:9] offset:1024 nt
	global_load_dwordx2 v[144:145], v184, s[6:7] offset:2048 nt
	global_load_dwordx2 v[2:3], v184, s[8:9] offset:2048 nt
	s_lshl_b64 s[4:5], s[4:5], 8
	v_readlane_b32 s6, v254, 52
	v_readlane_b32 s7, v254, 53
	s_add_u32 s4, s6, s4
	s_addc_u32 s5, s7, s5
	s_cmp_gt_u32 s25, 3
	s_cselect_b32 s1, 39, 3
	s_add_i32 s1, s1, s24
	s_add_i32 s1, s1, 3
	global_load_dwordx4 v[72:75], v0, s[4:5]
	s_and_b64 s[4:5], s[90:91], exec
	s_cselect_b32 s1, s25, s1
	s_lshl_b32 s1, s1, 3
	s_add_i32 s1, s34, s1
	v_mov_b32_e32 v0, s1
	v_add_u32_e32 v164, v201, v121
	ds_read_b32 v0, v0 offset:46080
	ds_read_b128 v[104:107], v164
	ds_read_b128 v[108:111], v164 offset:64
	ds_read_b128 v[212:215], v164 offset:2304
	ds_read_b128 v[216:219], v164 offset:2368
	ds_read_b128 v[224:227], v164 offset:4608
	ds_read_b128 v[242:245], v164 offset:4672
	s_waitcnt lgkmcnt(5)
	v_mfma_f32_16x16x32_bf16 v[104:107], v[40:43], v[104:107], 0
	v_lshlrev_b32_e32 v112, 16, v92
	v_and_b32_e32 v113, 0xffff0000, v92
	v_lshlrev_b32_e32 v92, 16, v93
	s_waitcnt lgkmcnt(4)
	v_mfma_f32_16x16x32_bf16 v[104:107], v[36:39], v[108:111], v[104:107]
	v_and_b32_e32 v93, 0xffff0000, v93
	v_lshlrev_b32_e32 v114, 16, v96
	v_and_b32_e32 v115, 0xffff0000, v96
	v_lshlrev_b32_e32 v96, 16, v97
	v_and_b32_e32 v97, 0xffff0000, v97
	v_pk_fma_f32 v[150:151], v[150:151], v[0:1], v[92:93] op_sel_hi:[1,0,1]
	s_nop 1
	v_pk_fma_f32 v[92:93], v[62:63], v[106:107], v[96:97]
	v_pk_fma_f32 v[96:97], v[60:61], v[104:105], v[114:115]
	s_waitcnt lgkmcnt(3)
	v_mfma_f32_16x16x32_bf16 v[104:107], v[40:43], v[212:215], 0
	v_fma_f32 v148, v148, v0, v112
	v_fma_f32 v149, v149, v0, v113
	v_lshlrev_b32_e32 v112, 16, v94
	v_and_b32_e32 v113, 0xffff0000, v94
	s_waitcnt lgkmcnt(2)
	v_mfma_f32_16x16x32_bf16 v[104:107], v[36:39], v[216:219], v[104:107]
	ds_read_b128 v[212:215], v164 offset:6912
	ds_read_b128 v[216:219], v164 offset:6976
	v_lshlrev_b32_e32 v94, 16, v95
	v_and_b32_e32 v95, 0xffff0000, v95
	v_lshlrev_b32_e32 v114, 16, v98
	v_and_b32_e32 v115, 0xffff0000, v98
	v_lshlrev_b32_e32 v98, 16, v99
	v_and_b32_e32 v99, 0xffff0000, v99
	v_pk_fma_f32 v[152:153], v[152:153], v[0:1], v[94:95] op_sel_hi:[1,0,1]
	s_nop 0
	v_pk_fma_f32 v[94:95], v[62:63], v[106:107], v[98:99]
	v_pk_fma_f32 v[98:99], v[60:61], v[104:105], v[114:115]
	s_waitcnt lgkmcnt(3)
	v_mfma_f32_16x16x32_bf16 v[104:107], v[40:43], v[224:227], 0
	v_fma_f32 v154, v154, v0, v112
	v_fma_f32 v155, v155, v0, v113
	v_lshlrev_b32_e32 v112, 16, v64
	v_and_b32_e32 v113, 0xffff0000, v64
	s_waitcnt lgkmcnt(2)
	v_mfma_f32_16x16x32_bf16 v[104:107], v[36:39], v[242:245], v[104:107]
	ds_read_b128 v[224:227], v164 offset:9216
	ds_read_b128 v[242:245], v164 offset:9280
	v_lshlrev_b32_e32 v114, 16, v68
	v_and_b32_e32 v115, 0xffff0000, v68
	v_lshlrev_b32_e32 v68, 16, v69
	v_and_b32_e32 v69, 0xffff0000, v69
	v_pk_fma_f32 v[158:159], v[158:159], v[0:1], v[112:113] op_sel_hi:[1,0,1]
	s_nop 2
	v_pk_fma_f32 v[116:117], v[62:63], v[106:107], v[68:69]
	v_pk_fma_f32 v[112:113], v[60:61], v[104:105], v[114:115]
	v_lshlrev_b32_e32 v64, 16, v65
	v_and_b32_e32 v65, 0xffff0000, v65
	v_pk_fma_f32 v[156:157], v[156:157], v[0:1], v[64:65] op_sel_hi:[1,0,1]
	v_lshlrev_b32_e32 v68, 16, v66
	v_and_b32_e32 v69, 0xffff0000, v66
	v_lshlrev_b32_e32 v114, 16, v67
	v_and_b32_e32 v115, 0xffff0000, v67
	s_waitcnt lgkmcnt(3)
	v_mfma_f32_16x16x32_bf16 v[64:67], v[40:43], v[212:215], 0
	v_lshlrev_b32_e32 v118, 16, v70
	v_and_b32_e32 v119, 0xffff0000, v70
	v_lshlrev_b32_e32 v70, 16, v71
	s_waitcnt lgkmcnt(2)
	v_mfma_f32_16x16x32_bf16 v[64:67], v[36:39], v[216:219], v[64:67]
	v_and_b32_e32 v71, 0xffff0000, v71
	v_pk_fma_f32 v[162:163], v[162:163], v[0:1], v[68:69] op_sel_hi:[1,0,1]
	v_lshlrev_b32_e32 v108, 16, v142
	v_and_b32_e32 v109, 0xffff0000, v142
	v_lshlrev_b32_e32 v104, 16, v146
	s_nop 2
	v_pk_fma_f32 v[166:167], v[62:63], v[66:67], v[70:71]
	v_pk_fma_f32 v[118:119], v[60:61], v[64:65], v[118:119]
	s_waitcnt lgkmcnt(1)
	v_mfma_f32_16x16x32_bf16 v[40:43], v[40:43], v[224:227], 0
	v_and_b32_e32 v105, 0xffff0000, v146
	v_lshlrev_b32_e32 v106, 16, v147
	v_and_b32_e32 v107, 0xffff0000, v147
	s_waitcnt lgkmcnt(0)
	v_mfma_f32_16x16x32_bf16 v[36:39], v[36:39], v[242:245], v[40:43]
	v_fma_f32 v160, v160, v0, v114
	v_fma_f32 v161, v161, v0, v115
	v_pk_fma_f32 v[178:179], v[182:183], v[0:1], v[106:107] op_sel_hi:[1,0,1]
	v_pk_fma_f32 v[164:165], v[180:181], v[0:1], v[104:105] op_sel_hi:[1,0,1]
	v_lshlrev_b32_e32 v110, 16, v143
	v_and_b32_e32 v111, 0xffff0000, v143
	s_nop 1
	v_pk_fma_f32 v[36:37], v[60:61], v[36:37], v[108:109]
	v_pk_fma_f32 v[38:39], v[62:63], v[38:39], v[110:111]
	s_nop 0
	v_mov_b32_dpp v0, v36 row_newbcast:1 row_mask:0xf bank_mask:0xf bound_ctrl:1
	v_max_f32_dpp v0, |v36|, v0 row_newbcast:0 row_mask:0xf bank_mask:0xf bound_ctrl:1
	v_rcp_f32_e32 v36, v0
	s_nop 0
	v_mov_b32_dpp v0, v37 row_newbcast:1 row_mask:0xf bank_mask:0xf bound_ctrl:1
	v_max_f32_dpp v0, |v37|, v0 row_newbcast:0 row_mask:0xf bank_mask:0xf bound_ctrl:1
	v_rcp_f32_e32 v37, v0
	s_nop 0
	v_mov_b32_dpp v0, v38 row_newbcast:1 row_mask:0xf bank_mask:0xf bound_ctrl:1
	v_max_f32_dpp v0, |v38|, v0 row_newbcast:0 row_mask:0xf bank_mask:0xf bound_ctrl:1
	v_rcp_f32_e32 v38, v0
	v_pk_mul_f32 v[104:105], v[96:97], v[36:37]
	v_mov_b32_dpp v0, v39 row_newbcast:1 row_mask:0xf bank_mask:0xf bound_ctrl:1
	v_max_f32_dpp v0, |v39|, v0 row_newbcast:0 row_mask:0xf bank_mask:0xf bound_ctrl:1
	v_rcp_f32_e32 v39, v0
	v_pk_mul_f32 v[108:109], v[98:99], v[36:37]
	v_pk_mul_f32 v[112:113], v[112:113], v[36:37]
	v_pk_mul_f32 v[106:107], v[92:93], v[38:39]
	v_pk_mul_f32 v[110:111], v[94:95], v[38:39]
	v_pk_mul_f32 v[114:115], v[116:117], v[38:39]
	v_pk_mul_f32 v[116:117], v[118:119], v[36:37]
	v_pk_mul_f32 v[118:119], v[166:167], v[38:39]

; template <int N> __device__ __forceinline__ float row16_bcast(float v) { return dppf<0x150 + N>(v); }
; __device__ __forceinline__ float frcp(float x) { return __builtin_amdgcn_rcpf(x); }
;     ...
;             f32x4 o = {0.f, 0.f, 0.f, 0.f};
;             o = __builtin_amdgcn_mfma_f32_16x16x32_bf16(use.Qf[0], s0, o, 0, 0, 0); o = __builtin_amdgcn_mfma_f32_16x16x32_bf16(use.Qf[1], s1, o, 0, 0, 0);
;             S[t] = S[t] * gl + bv; O[t] = o * use.wi + ov; }
;     }
;     if (!GDN) {
; #pragma unroll
;         for (int i = 0; i < 4; ++i) { const float den = row16_bcast<0>(O[NT - 1][i]), fl = row16_bcast<1>(O[NT - 1][i]); const float dv = frcp(fmaxf(fabsf(den), fl));
; #pragma unroll
;             for (int t = 0; t < 4; ++t) O[t][i] *= dv; }
.LBB0_402:
	v_lshlrev_b32_e32 v168, 16, v53
	v_and_b32_e32 v169, 0xffff0000, v53
	v_pk_fma_f32 v[168:169], v[102:103], v[106:107], v[168:169]
	v_lshlrev_b32_e32 v106, 16, v55
	v_and_b32_e32 v107, 0xffff0000, v55
	v_pk_fma_f32 v[170:171], v[102:103], v[110:111], v[106:107]
	v_lshlrev_b32_e32 v106, 16, v33
	v_and_b32_e32 v107, 0xffff0000, v33
	v_pk_fma_f32 v[172:173], v[102:103], v[114:115], v[106:107]
	v_lshlrev_b32_e32 v106, 16, v35
	v_and_b32_e32 v107, 0xffff0000, v35
	v_pk_fma_f32 v[174:175], v[102:103], v[118:119], v[106:107]
	v_lshlrev_b32_e32 v166, 16, v52
	v_and_b32_e32 v167, 0xffff0000, v52
	v_max_f32_e64 v106, |v187|, v193
	v_pk_fma_f32 v[166:167], v[100:101], v[104:105], v[166:167]
	v_lshlrev_b32_e32 v104, 16, v54
	v_and_b32_e32 v105, 0xffff0000, v54
	v_rcp_f32_e32 v106, v106
	v_pk_fma_f32 v[108:109], v[100:101], v[108:109], v[104:105]
	v_lshlrev_b32_e32 v104, 16, v32
	v_and_b32_e32 v105, 0xffff0000, v32
	v_pk_fma_f32 v[110:111], v[100:101], v[112:113], v[104:105]
	v_lshlrev_b32_e32 v104, 16, v34
	v_and_b32_e32 v105, 0xffff0000, v34
	v_pk_fma_f32 v[114:115], v[100:101], v[116:117], v[104:105]
	v_mov_b32_e32 v104, v166
	v_mov_b32_e32 v105, v108
	v_pk_mul_f32 v[104:105], v[104:105], v[106:107] op_sel_hi:[1,0]
	v_max_f32_e64 v107, |v179|, v186
	v_mov_b32_e32 v112, v110
	v_rcp_f32_e32 v110, v107
	v_mov_b32_e32 v113, v114
	v_mov_b32_e32 v108, v167
	v_pk_mul_f32 v[106:107], v[112:113], v[106:107] op_sel_hi:[1,0]
	v_pk_mul_f32 v[112:113], v[108:109], v[110:111] op_sel_hi:[1,0]
	v_max_f32_e64 v108, |v165|, v178
	v_rcp_f32_e32 v116, v108
	v_mov_b32_e32 v114, v111
	v_mov_b32_e32 v108, v168
	v_mov_b32_e32 v109, v170
	v_pk_mul_f32 v[114:115], v[114:115], v[110:111] op_sel_hi:[1,0]
	v_pk_mul_f32 v[108:109], v[108:109], v[116:117] op_sel_hi:[1,0]
	v_max_f32_e64 v111, |v163|, v164
	v_rcp_f32_e32 v164, v111
	s_cmp_gt_u32 s25, 2
	v_mov_b32_e32 v110, v172
	v_mov_b32_e32 v111, v174
	v_mov_b32_e32 v170, v169
	v_mov_b32_e32 v174, v173
	s_cselect_b32 s6, 20, 2
	v_pk_mul_f32 v[110:111], v[110:111], v[116:117] op_sel_hi:[1,0]
	v_pk_mul_f32 v[118:119], v[170:171], v[164:165] op_sel_hi:[1,0]
	v_pk_mul_f32 v[116:117], v[174:175], v[164:165] op_sel_hi:[1,0]
	s_cmp_lt_u32 s4, s6
	s_mov_b64 s[10:11], -1
	s_waitcnt lgkmcnt(0)
	s_barrier
	s_cbranch_scc1 .LBB0_410
; __device__ __forceinline__ float row16_sum(float v) { v += dppf<0xB1>(v); v += dppf<0x4E>(v); v += dppf<0x141>(v); v += dppf<0x140>(v); return v; }
; __device__ __forceinline__ float frsq(float x) { return __builtin_amdgcn_rsqf(x); }
; __device__ __forceinline__ v2u pack4(const f32x4 v) { v2u r; r.x = pk2(v[0], v[1]); r.y = pk2(v[2], v[3]); return r; }
; __device__ __forceinline__ f32x4 unpack4(const v2u w) { f32x4 r; r[0] = bflo(w.x); r[1] = bfhi(w.x); r[2] = bflo(w.y); r[3] = bfhi(w.y); return r; }
; __device__ __forceinline__ const char* upin(const char* p) { asm volatile("" : "+s"(p)); return p; }
; __device__ __forceinline__ char* upin(char* p) { asm volatile("" : "+s"(p)); return p; }
; template <bool GDN> __device__ __forceinline__ void scan_finish(const Frame& F, int b, int h, int dir, const ScanLane& L, int s, float* PEND, const f32x4 (&Oin)[4], const ScanFin& f) {
;     ...
;         f32x4 O[4]; float ss[4] = {0.f, 0.f, 0.f, 0.f};
; #pragma unroll
;         for (int t = 0; t < 4; ++t)
;             { const f32x4 pv = unpack4(f.pend[t]);
; #pragma unroll
;             for (int i = 0; i < 4; ++i) { O[t][i] = Oin[t][i] + pv[i]; ss[i] += O[t][i] * O[t][i]; } }
; #pragma unroll
;         for (int i = 0; i < 4; ++i) ss[i] = frsq(row16_sum(ss[i]) * (1.f / 64.f) + EPS);
;         char* mp = (char*)F.MIX + ((size_t)row0 * 1024 + (GDN ? 0 : 768) + h * 64) * 2;
; #pragma unroll
;         for (int i = 0; i < 4; ++i) { const f32x4 g = unpack4(f.gz[i]); f32x4 ov;
; #pragma unroll
;             for (int t = 0; t < 4; ++t) ov[t] = O[t][i] * ss[i] * g[t];
;             stu<v2u>(upin(mp + i * 2048), L.mix, pack4(ov)); }
	s_lshl_b32 s4, s5, 6
	s_cmp_lt_i32 s5, 4
	s_cselect_b32 s6, s63, s33
	s_add_i32 s6, s6, s4
	s_ashr_i32 s7, s6, 31
	s_lshl_b64 s[6:7], s[6:7], 11
	s_add_u32 s4, s26, s6
	s_addc_u32 s8, s27, s7
	s_add_u32 s6, s4, 0x600
	s_addc_u32 s7, s8, 0
	v_lshlrev_b32_e32 v246, 16, v12
	v_lshlrev_b32_e32 v247, 16, v14
	v_lshlrev_b32_e32 v220, 16, v16
	v_lshlrev_b32_e32 v221, 16, v18
	v_pk_add_f32 v[212:213], v[104:105], v[246:247]
	v_pk_add_f32 v[214:215], v[106:107], v[220:221]
	v_pk_mul_f32 v[204:205], v[212:213], v[212:213]
	v_pk_fma_f32 v[204:205], v[214:215], v[214:215], v[204:205]
	v_and_b32_e32 v246, 0xffff0000, v12
	v_and_b32_e32 v247, 0xffff0000, v14
	v_and_b32_e32 v220, 0xffff0000, v16
	v_and_b32_e32 v221, 0xffff0000, v18
	v_pk_add_f32 v[216:217], v[112:113], v[246:247]
	v_pk_add_f32 v[218:219], v[114:115], v[220:221]
	v_pk_mul_f32 v[206:207], v[216:217], v[216:217]
	v_pk_fma_f32 v[206:207], v[218:219], v[218:219], v[206:207]
	v_lshlrev_b32_e32 v246, 16, v13
	v_lshlrev_b32_e32 v247, 16, v15
	v_lshlrev_b32_e32 v220, 16, v17
	v_lshlrev_b32_e32 v221, 16, v19
	v_pk_add_f32 v[224:225], v[108:109], v[246:247]
	v_pk_add_f32 v[226:227], v[110:111], v[220:221]
	v_pk_mul_f32 v[208:209], v[224:225], v[224:225]
	v_pk_fma_f32 v[208:209], v[226:227], v[226:227], v[208:209]
	v_and_b32_e32 v246, 0xffff0000, v13
	v_and_b32_e32 v247, 0xffff0000, v15
	v_and_b32_e32 v220, 0xffff0000, v17
	v_and_b32_e32 v221, 0xffff0000, v19
	v_pk_add_f32 v[242:243], v[118:119], v[246:247]
	v_pk_add_f32 v[244:245], v[116:117], v[220:221]
	v_pk_mul_f32 v[210:211], v[242:243], v[242:243]
	v_pk_fma_f32 v[210:211], v[244:245], v[244:245], v[210:211]
	v_add_f32_e32 v204, v204, v205
	v_add_f32_e32 v206, v206, v207
	v_add_f32_e32 v208, v208, v209
	v_add_f32_e32 v210, v210, v211
	s_nop 0
	v_add_f32_dpp v204, v204, v204 quad_perm:[1,0,3,2] row_mask:0xf bank_mask:0xf bound_ctrl:1
	v_add_f32_dpp v206, v206, v206 quad_perm:[1,0,3,2] row_mask:0xf bank_mask:0xf bound_ctrl:1
	v_add_f32_dpp v208, v208, v208 quad_perm:[1,0,3,2] row_mask:0xf bank_mask:0xf bound_ctrl:1
	v_add_f32_dpp v210, v210, v210 quad_perm:[1,0,3,2] row_mask:0xf bank_mask:0xf bound_ctrl:1
	v_add_f32_dpp v204, v204, v204 quad_perm:[2,3,0,1] row_mask:0xf bank_mask:0xf bound_ctrl:1
	v_add_f32_dpp v206, v206, v206 quad_perm:[2,3,0,1] row_mask:0xf bank_mask:0xf bound_ctrl:1
	v_add_f32_dpp v208, v208, v208 quad_perm:[2,3,0,1] row_mask:0xf bank_mask:0xf bound_ctrl:1
	v_add_f32_dpp v210, v210, v210 quad_perm:[2,3,0,1] row_mask:0xf bank_mask:0xf bound_ctrl:1
	v_add_f32_dpp v204, v204, v204 row_half_mirror row_mask:0xf bank_mask:0xf bound_ctrl:1
	v_add_f32_dpp v206, v206, v206 row_half_mirror row_mask:0xf bank_mask:0xf bound_ctrl:1
	v_add_f32_dpp v208, v208, v208 row_half_mirror row_mask:0xf bank_mask:0xf bound_ctrl:1
	v_add_f32_dpp v210, v210, v210 row_half_mirror row_mask:0xf bank_mask:0xf bound_ctrl:1
	v_add_f32_dpp v204, v204, v204 row_mirror row_mask:0xf bank_mask:0xf bound_ctrl:1
	v_add_f32_dpp v206, v206, v206 row_mirror row_mask:0xf bank_mask:0xf bound_ctrl:1
	v_add_f32_dpp v208, v208, v208 row_mirror row_mask:0xf bank_mask:0xf bound_ctrl:1
	v_add_f32_dpp v210, v210, v210 row_mirror row_mask:0xf bank_mask:0xf bound_ctrl:1
	v_fmamk_f32 v204, v204, 0x3c800000, v231
	v_fmamk_f32 v206, v206, 0x3c800000, v231
	v_fmamk_f32 v208, v208, 0x3c800000, v231
	v_fmamk_f32 v210, v210, 0x3c800000, v231
	v_rsq_f32_e32 v204, v204
	v_rsq_f32_e32 v206, v206
	v_rsq_f32_e32 v208, v208
	v_rsq_f32_e32 v210, v210
	v_lshlrev_b32_e32 v246, 16, v130
	v_and_b32_e32 v247, 0xffff0000, v130
	v_lshlrev_b32_e32 v220, 16, v131
	v_and_b32_e32 v221, 0xffff0000, v131
	v_pk_mul_f32 v[212:213], v[212:213], v[204:205] op_sel_hi:[1,0]
	v_pk_mul_f32 v[214:215], v[214:215], v[204:205] op_sel_hi:[1,0]
	v_pk_mul_f32 v[212:213], v[212:213], v[246:247]
	v_pk_mul_f32 v[214:215], v[214:215], v[220:221]
	v_lshlrev_b32_e32 v246, 16, v132
	v_and_b32_e32 v247, 0xffff0000, v132
	v_lshlrev_b32_e32 v220, 16, v133
	v_and_b32_e32 v221, 0xffff0000, v133
	v_pk_mul_f32 v[216:217], v[216:217], v[206:207] op_sel_hi:[1,0]
	v_pk_mul_f32 v[218:219], v[218:219], v[206:207] op_sel_hi:[1,0]
	v_pk_mul_f32 v[216:217], v[216:217], v[246:247]
	v_pk_mul_f32 v[218:219], v[218:219], v[220:221]
	v_lshlrev_b32_e32 v246, 16, v134
	v_and_b32_e32 v247, 0xffff0000, v134
	v_lshlrev_b32_e32 v220, 16, v135
	v_and_b32_e32 v221, 0xffff0000, v135
	v_pk_mul_f32 v[224:225], v[224:225], v[208:209] op_sel_hi:[1,0]
	v_pk_mul_f32 v[226:227], v[226:227], v[208:209] op_sel_hi:[1,0]
	v_pk_mul_f32 v[224:225], v[224:225], v[246:247]
	v_pk_mul_f32 v[226:227], v[226:227], v[220:221]
	v_lshlrev_b32_e32 v246, 16, v136
	v_and_b32_e32 v247, 0xffff0000, v136
	v_lshlrev_b32_e32 v220, 16, v137
	v_and_b32_e32 v221, 0xffff0000, v137
	v_pk_mul_f32 v[242:243], v[242:243], v[210:211] op_sel_hi:[1,0]
	v_pk_mul_f32 v[244:245], v[244:245], v[210:211] op_sel_hi:[1,0]
	v_pk_mul_f32 v[242:243], v[242:243], v[246:247]
	v_pk_mul_f32 v[244:245], v[244:245], v[220:221]
	v_cvt_pk_bf16_f32 v204, v212, v213
	v_cvt_pk_bf16_f32 v205, v214, v215
	v_cvt_pk_bf16_f32 v210, v216, v217
	v_cvt_pk_bf16_f32 v211, v218, v219
	v_cvt_pk_bf16_f32 v206, v224, v225
	v_cvt_pk_bf16_f32 v207, v226, v227
	v_cvt_pk_bf16_f32 v218, v242, v243
	v_cvt_pk_bf16_f32 v219, v244, v245
	v_and_b32_e32 v220, 1, v232
	v_mul_u32_u24_e32 v220, 0x7f8, v220
	v_add_u32_e32 v220, v162, v220
	s_mov_b32 vcc_lo, 0x55555555
	s_mov_b32 vcc_hi, 0x55555555
	v_cndmask_b32_dpp v208, v210, v204, vcc quad_perm:[1,0,3,2] row_mask:0xf bank_mask:0xf
	v_cndmask_b32_dpp v209, v211, v205, vcc quad_perm:[1,0,3,2] row_mask:0xf bank_mask:0xf
	v_cndmask_b32_dpp v216, v218, v206, vcc quad_perm:[1,0,3,2] row_mask:0xf bank_mask:0xf
	v_cndmask_b32_dpp v217, v219, v207, vcc quad_perm:[1,0,3,2] row_mask:0xf bank_mask:0xf
	s_not_b64 vcc, vcc
	v_cndmask_b32_dpp v210, v204, v210, vcc quad_perm:[1,0,3,2] row_mask:0xf bank_mask:0xf
	v_cndmask_b32_dpp v211, v205, v211, vcc quad_perm:[1,0,3,2] row_mask:0xf bank_mask:0xf
	v_cndmask_b32_dpp v218, v206, v218, vcc quad_perm:[1,0,3,2] row_mask:0xf bank_mask:0xf
	v_cndmask_b32_dpp v219, v207, v219, vcc quad_perm:[1,0,3,2] row_mask:0xf bank_mask:0xf
	global_store_dwordx4 v220, v[208:211], s[6:7]
	s_add_u32 s6, s4, 0xe00
	s_addc_u32 s7, s8, 0
	s_add_u32 s6, s4, 0x1600
	s_addc_u32 s7, s8, 0
	global_store_dwordx4 v220, v[216:219], s[6:7]
	s_add_u32 s6, s4, 0x1e00
	s_addc_u32 s7, s8, 0
	s_cbranch_execz .LBB0_411

; template <bool GDN, int NT> __device__ __forceinline__ void scan_load(const Frame& F, int b, int h, int dir, const ScanLane& L, int s, ScanOps<NT>& o) {
;     ...
;         const char* zq = upin((const char*)F.Z + ((size_t)chunk_row0(b, cidx) * ZW + ZC_LQ + h * 64) * 2);
; #pragma unroll
;         for (int ks = 0; ks < 2; ++ks) { o.Qf[ks] = ldu<bf16x8>(zq + ks * 64, L.zq); o.Mf[ks] = o.Qf[ks]; }
;         const char* base = (const char*)F.PM + (size_t)ud * 20480;
;         const char* bO = upin(base); const char* bB = upin(base + 10240);
; #pragma unroll
;         for (int pr = 0; pr < 2; ++pr) { const v4u qb = ldun<v4u>(bB + pr * 1024, L.o16p), qo = ldun<v4u>(bO + pr * 1024, L.o16p);
;             o.bv[2 * pr] = (v2u){qb.x, qb.y}; o.bv[2 * pr + 1] = (v2u){qb.z, qb.w}; o.ov[2 * pr] = (v2u){qo.x, qo.y}; o.ov[2 * pr + 1] = (v2u){qo.z, qo.w}; }
;         o.bv[4] = ldun<v2u>(bB + 2048, L.o8); o.ov[4] = ldun<v2u>(bO + 2048, L.o8);
;         o.wi = ldu<f32x4>(upin((const char*)F.WI + (size_t)ud * 256), L.wi);
;     ...
;     const float gl = ((const LAS float*)(St + 4 * 80 * 72))[(dir ? (s < 4 ? 3 - s : 39 - s) : s) * 2 + dir];
;     f32x4 O[NT];
; #pragma unroll
;     for (int t = 0; t < NT; ++t) {
;         const LAS bf16_t* sp2 = Sb + (16 * t + lr) * 72 + 8 * lq;
;         const bf16x8 s0 = *(const LAS bf16x8*)sp2, s1 = *(const LAS bf16x8*)(sp2 + 32);
;         const f32x4 bv = unpack4(use.bv[t]), ov = unpack4(use.ov[t]);
;         if (GDN) {
;             f32x4 o = ov, sn = S[t] * gl + bv;
;             o = __builtin_amdgcn_mfma_f32_16x16x32_bf16(use.Qf[0], s0, o, 0, 0, 0); o = __builtin_amdgcn_mfma_f32_16x16x32_bf16(use.Qf[1], s1, o, 0, 0, 0);
;             sn = __builtin_amdgcn_mfma_f32_16x16x32_bf16(use.Mf[0], s0, sn, 0, 0, 0); sn = __builtin_amdgcn_mfma_f32_16x16x32_bf16(use.Mf[1], s1, sn, 0, 0, 0);
;             S[t] = sn; O[t] = o;
;         } else {
;             f32x4 o = {0.f, 0.f, 0.f, 0.f};
;             o = __builtin_amdgcn_mfma_f32_16x16x32_bf16(use.Qf[0], s0, o, 0, 0, 0); o = __builtin_amdgcn_mfma_f32_16x16x32_bf16(use.Qf[1], s1, o, 0, 0, 0);
;             S[t] = S[t] * gl + bv; O[t] = o * use.wi + ov; }
;     }
;     if (!GDN) {
; #pragma unroll
;         for (int i = 0; i < 4; ++i) { const float den = row16_bcast<0>(O[NT - 1][i]), fl = row16_bcast<1>(O[NT - 1][i]); const float dv = frcp(fmaxf(fabsf(den), fl));
; #pragma unroll
.LBB0_409:
	s_min_u32 s5, s3, 33
	s_add_i32 s8, s5, 2
	s_sub_i32 s5, 37, s5
	s_and_b64 s[6:7], s[90:91], exec
	s_cselect_b32 s5, s8, s5
	s_lshl_b32 s6, s5, 6
	s_add_i32 s6, s6, s33
	s_add_i32 s5, s5, s31
	s_mulk_i32 s6, 0xd00
	s_lshl_b32 s5, s5, 1
	s_or_b32 s6, s36, s6
	s_mov_b32 s7, s37
	s_add_i32 s92, s5, s68
	s_lshl_b64 s[6:7], s[6:7], 1
	s_add_u32 s6, s16, s6
	s_addc_u32 s7, s17, s7
	global_load_dwordx4 v[24:27], v190, s[6:7]
	global_load_dwordx4 v[20:23], v190, s[6:7] offset:64
	s_mul_i32 s6, s92, 0x5000
	v_readlane_b32 s7, v254, 46
	s_mul_hi_u32 s5, s92, 0x5000
	s_add_u32 s6, s7, s6
	v_readlane_b32 s7, v254, 47
	s_addc_u32 s7, s7, s5
	s_mov_b64 s[8:9], s[6:7]
	s_add_u32 s6, s6, 0x2800
	s_addc_u32 s7, s7, 0
	s_nop 0
	global_load_dwordx4 v[44:47], v189, s[6:7] nt
	global_load_dwordx4 v[28:31], v189, s[6:7] offset:1024 nt
	global_load_dwordx4 v[52:55], v189, s[8:9] nt
	global_load_dwordx4 v[32:35], v189, s[8:9] offset:1024 nt
	global_load_dwordx2 v[140:141], v188, s[6:7] offset:2048 nt
	global_load_dwordx2 v[138:139], v188, s[8:9] offset:2048 nt
	s_lshl_b64 s[6:7], s[92:93], 8
	v_readlane_b32 s8, v254, 52
	v_readlane_b32 s9, v254, 53
	s_add_u32 s6, s8, s6
	s_addc_u32 s7, s9, s7
	global_load_dwordx4 v[100:103], v0, s[6:7]
	s_add_i32 s6, s4, 1
	s_and_b64 s[4:5], s[90:91], exec
	s_cselect_b32 s4, s3, s6
	s_lshl_b32 s4, s4, 3
	s_add_i32 s4, s34, s4
	v_mov_b32_e32 v0, s4
	ds_read_b32 v0, v0 offset:46080
	ds_read_b128 v[204:207], v203
	ds_read_b128 v[208:211], v203 offset:64
	ds_read_b128 v[212:215], v203 offset:2304
	ds_read_b128 v[216:219], v203 offset:2368
	ds_read_b128 v[224:227], v203 offset:4608
	ds_read_b128 v[242:245], v203 offset:4672
	s_waitcnt lgkmcnt(5)
	v_mfma_f32_16x16x32_bf16 v[204:207], v[56:59], v[204:207], 0
	v_lshlrev_b32_e32 v112, 16, v84
	v_and_b32_e32 v113, 0xffff0000, v84
	v_lshlrev_b32_e32 v84, 16, v85
	s_waitcnt lgkmcnt(4)
	v_mfma_f32_16x16x32_bf16 v[204:207], v[48:51], v[208:211], v[204:207]
	v_and_b32_e32 v85, 0xffff0000, v85
	v_lshlrev_b32_e32 v114, 16, v88
	v_and_b32_e32 v115, 0xffff0000, v88
	v_lshlrev_b32_e32 v88, 16, v89
	v_and_b32_e32 v89, 0xffff0000, v89
	v_pk_fma_f32 v[180:181], v[180:181], v[0:1], v[84:85] op_sel_hi:[1,0,1]
	s_nop 1
	v_pk_fma_f32 v[84:85], v[72:73], v[204:205], v[114:115]
	v_pk_fma_f32 v[88:89], v[74:75], v[206:207], v[88:89]
	s_waitcnt lgkmcnt(3)
	v_mfma_f32_16x16x32_bf16 v[204:207], v[56:59], v[212:215], 0
	v_fma_f32 v182, v182, v0, v112
	v_fma_f32 v183, v183, v0, v113
	v_lshlrev_b32_e32 v112, 16, v86
	v_and_b32_e32 v113, 0xffff0000, v86
	s_waitcnt lgkmcnt(2)
	v_mfma_f32_16x16x32_bf16 v[204:207], v[48:51], v[216:219], v[204:207]
	ds_read_b128 v[212:215], v203 offset:6912
	ds_read_b128 v[216:219], v203 offset:6976
	v_lshlrev_b32_e32 v86, 16, v87
	v_and_b32_e32 v87, 0xffff0000, v87
	v_lshlrev_b32_e32 v114, 16, v90
	v_and_b32_e32 v115, 0xffff0000, v90
	v_lshlrev_b32_e32 v90, 16, v91
	v_and_b32_e32 v91, 0xffff0000, v91
	v_pk_fma_f32 v[150:151], v[150:151], v[0:1], v[86:87] op_sel_hi:[1,0,1]
	s_nop 0
	v_pk_fma_f32 v[86:87], v[72:73], v[204:205], v[114:115]
	v_pk_fma_f32 v[90:91], v[74:75], v[206:207], v[90:91]
	s_waitcnt lgkmcnt(3)
	v_mfma_f32_16x16x32_bf16 v[204:207], v[56:59], v[224:227], 0
	v_fma_f32 v154, v154, v0, v112
	v_fma_f32 v155, v155, v0, v113
	v_lshlrev_b32_e32 v112, 16, v76
	v_and_b32_e32 v113, 0xffff0000, v76
	s_waitcnt lgkmcnt(2)
	v_mfma_f32_16x16x32_bf16 v[204:207], v[48:51], v[242:245], v[204:207]
	ds_read_b128 v[224:227], v203 offset:9216
	ds_read_b128 v[242:245], v203 offset:9280
	v_lshlrev_b32_e32 v76, 16, v77
	v_and_b32_e32 v77, 0xffff0000, v77
	v_lshlrev_b32_e32 v114, 16, v80
	v_and_b32_e32 v115, 0xffff0000, v80
	v_lshlrev_b32_e32 v80, 16, v81
	v_and_b32_e32 v81, 0xffff0000, v81
	v_pk_fma_f32 v[148:149], v[148:149], v[0:1], v[76:77] op_sel_hi:[1,0,1]
	s_nop 0
	v_pk_fma_f32 v[76:77], v[72:73], v[204:205], v[114:115]
	v_pk_fma_f32 v[80:81], v[74:75], v[206:207], v[80:81]
	s_waitcnt lgkmcnt(3)
	v_mfma_f32_16x16x32_bf16 v[204:207], v[56:59], v[212:215], 0
	v_fma_f32 v152, v152, v0, v112
	v_fma_f32 v153, v153, v0, v113
	v_lshlrev_b32_e32 v112, 16, v78
	v_and_b32_e32 v113, 0xffff0000, v78
	s_waitcnt lgkmcnt(2)
	v_mfma_f32_16x16x32_bf16 v[204:207], v[48:51], v[216:219], v[204:207]
	v_lshlrev_b32_e32 v78, 16, v79
	v_and_b32_e32 v79, 0xffff0000, v79
	v_lshlrev_b32_e32 v114, 16, v82
	v_and_b32_e32 v115, 0xffff0000, v82
	v_lshlrev_b32_e32 v82, 16, v83
	v_and_b32_e32 v83, 0xffff0000, v83
	v_pk_fma_f32 v[184:185], v[184:185], v[0:1], v[78:79] op_sel_hi:[1,0,1]
	s_nop 0
	v_pk_fma_f32 v[78:79], v[72:73], v[204:205], v[114:115]
	v_pk_fma_f32 v[82:83], v[74:75], v[206:207], v[82:83]
	s_waitcnt lgkmcnt(1)
	v_mfma_f32_16x16x32_bf16 v[204:207], v[56:59], v[224:227], 0
	v_lshlrev_b32_e32 v116, 16, v2
	v_and_b32_e32 v117, 0xffff0000, v2
	v_lshlrev_b32_e32 v2, 16, v3
	s_waitcnt lgkmcnt(0)
	v_mfma_f32_16x16x32_bf16 v[204:207], v[48:51], v[242:245], v[204:207]
	v_and_b32_e32 v3, 0xffff0000, v3
	v_pk_fma_f32 v[160:161], v[160:161], v[0:1], v[112:113] op_sel_hi:[1,0,1]
	v_lshlrev_b32_e32 v112, 16, v144
	v_and_b32_e32 v113, 0xffff0000, v144
	v_lshlrev_b32_e32 v114, 16, v145
	s_nop 2
	v_pk_fma_f32 v[204:205], v[72:73], v[204:205], v[116:117]
	v_pk_fma_f32 v[2:3], v[74:75], v[206:207], v[2:3]
	v_and_b32_e32 v115, 0xffff0000, v145
	v_mov_b32_dpp v206, v204 row_newbcast:1 row_mask:0xf bank_mask:0xf bound_ctrl:1
	v_max_f32_dpp v204, |v204|, v206 row_newbcast:0 row_mask:0xf bank_mask:0xf bound_ctrl:1
	v_rcp_f32_e32 v204, v204
	v_mov_b32_dpp v206, v205 row_newbcast:1 row_mask:0xf bank_mask:0xf bound_ctrl:1
	v_max_f32_dpp v205, |v205|, v206 row_newbcast:0 row_mask:0xf bank_mask:0xf bound_ctrl:1
	v_rcp_f32_e32 v205, v205
	v_mov_b32_dpp v206, v2 row_newbcast:1 row_mask:0xf bank_mask:0xf bound_ctrl:1
	v_max_f32_dpp v2, |v2|, v206 row_newbcast:0 row_mask:0xf bank_mask:0xf bound_ctrl:1
	v_rcp_f32_e32 v206, v2
	v_pk_fma_f32 v[156:157], v[156:157], v[0:1], v[114:115] op_sel_hi:[1,0,1]
	v_mov_b32_dpp v2, v3 row_newbcast:1 row_mask:0xf bank_mask:0xf bound_ctrl:1
	v_max_f32_dpp v2, |v3|, v2 row_newbcast:0 row_mask:0xf bank_mask:0xf bound_ctrl:1
	v_rcp_f32_e32 v207, v2
	v_pk_fma_f32 v[158:159], v[158:159], v[0:1], v[112:113] op_sel_hi:[1,0,1]
	v_pk_mul_f32 v[50:51], v[84:85], v[204:205]
	v_pk_mul_f32 v[112:113], v[86:87], v[204:205]
	v_pk_mul_f32 v[2:3], v[88:89], v[206:207]
	v_pk_mul_f32 v[118:119], v[90:91], v[206:207]
	v_pk_mul_f32 v[48:49], v[80:81], v[206:207]
	v_pk_mul_f32 v[56:57], v[76:77], v[204:205]
	v_pk_mul_f32 v[116:117], v[82:83], v[206:207]
	v_pk_mul_f32 v[114:115], v[78:79], v[204:205]
	s_branch .LBB0_413

; template <int N> __device__ __forceinline__ float row16_bcast(float v) { return dppf<0x150 + N>(v); }
; __device__ __forceinline__ float frcp(float x) { return __builtin_amdgcn_rcpf(x); }
;     ...
;             f32x4 o = {0.f, 0.f, 0.f, 0.f};
;             o = __builtin_amdgcn_mfma_f32_16x16x32_bf16(use.Qf[0], s0, o, 0, 0, 0); o = __builtin_amdgcn_mfma_f32_16x16x32_bf16(use.Qf[1], s1, o, 0, 0, 0);
;             S[t] = S[t] * gl + bv; O[t] = o * use.wi + ov; }
;     }
;     if (!GDN) {
; #pragma unroll
;         for (int i = 0; i < 4; ++i) { const float den = row16_bcast<0>(O[NT - 1][i]), fl = row16_bcast<1>(O[NT - 1][i]); const float dv = frcp(fmaxf(fabsf(den), fl));
; #pragma unroll
;             for (int t = 0; t < 4; ++t) O[t][i] *= dv; }
.LBB0_441:
	v_lshlrev_b32_e32 v168, 16, v97
	v_and_b32_e32 v169, 0xffff0000, v97
	v_pk_fma_f32 v[168:169], v[62:63], v[106:107], v[168:169]
	v_lshlrev_b32_e32 v106, 16, v98
	v_and_b32_e32 v107, 0xffff0000, v98
	v_lshlrev_b32_e32 v166, 16, v96
	v_and_b32_e32 v167, 0xffff0000, v96
	v_pk_fma_f32 v[106:107], v[60:61], v[108:109], v[106:107]
	v_lshlrev_b32_e32 v108, 16, v68
	v_and_b32_e32 v109, 0xffff0000, v68
	v_pk_fma_f32 v[104:105], v[60:61], v[104:105], v[166:167]
	v_lshlrev_b32_e32 v166, 16, v99
	v_and_b32_e32 v167, 0xffff0000, v99
	v_pk_fma_f32 v[108:109], v[60:61], v[112:113], v[108:109]
	v_lshlrev_b32_e32 v112, 16, v70
	v_and_b32_e32 v113, 0xffff0000, v70
	v_pk_fma_f32 v[110:111], v[62:63], v[110:111], v[166:167]
	v_lshlrev_b32_e32 v166, 16, v69
	v_and_b32_e32 v167, 0xffff0000, v69
	v_pk_fma_f32 v[116:117], v[60:61], v[116:117], v[112:113]
	v_mov_b32_e32 v112, v104
	v_mov_b32_e32 v113, v106
	v_pk_fma_f32 v[166:167], v[62:63], v[114:115], v[166:167]
	v_lshlrev_b32_e32 v114, 16, v71
	v_and_b32_e32 v115, 0xffff0000, v71
	v_max_f32_e64 v104, |v160|, v161
	v_pk_fma_f32 v[170:171], v[62:63], v[118:119], v[114:115]
	v_mov_b32_e32 v118, v108
	v_rcp_f32_e32 v108, v104
	v_max_f32_e64 v114, |v184|, v185
	v_rcp_f32_e32 v114, v114
	v_mov_b32_e32 v106, v105
	v_pk_mul_f32 v[104:105], v[106:107], v[108:109] op_sel_hi:[1,0]
	v_mov_b32_e32 v119, v116
	v_max_f32_e64 v106, |v158|, v159
	v_pk_mul_f32 v[112:113], v[112:113], v[114:115] op_sel_hi:[1,0]
	v_pk_mul_f32 v[114:115], v[118:119], v[114:115] op_sel_hi:[1,0]
	v_rcp_f32_e32 v118, v106
	v_mov_b32_e32 v116, v109
	v_pk_mul_f32 v[106:107], v[116:117], v[108:109] op_sel_hi:[1,0]
	v_mov_b32_e32 v108, v168
	v_mov_b32_e32 v109, v110
	v_pk_mul_f32 v[116:117], v[108:109], v[118:119] op_sel_hi:[1,0]
	v_max_f32_e64 v109, |v156|, v157
	v_rcp_f32_e32 v156, v109
	v_mov_b32_e32 v108, v166
	v_mov_b32_e32 v109, v170
	v_mov_b32_e32 v110, v169
	v_mov_b32_e32 v170, v167
	v_pk_mul_f32 v[118:119], v[108:109], v[118:119] op_sel_hi:[1,0]
	v_pk_mul_f32 v[110:111], v[110:111], v[156:157] op_sel_hi:[1,0]
	v_pk_mul_f32 v[108:109], v[170:171], v[156:157] op_sel_hi:[1,0]
	s_cmp_lt_u32 s0, 16
	s_mov_b64 s[10:11], -1
	s_waitcnt lgkmcnt(0)
	s_barrier
	s_cbranch_scc1 .LBB0_453
; __device__ __forceinline__ float row16_sum(float v) { v += dppf<0xB1>(v); v += dppf<0x4E>(v); v += dppf<0x141>(v); v += dppf<0x140>(v); return v; }
; __device__ __forceinline__ float frsq(float x) { return __builtin_amdgcn_rsqf(x); }
; __device__ __forceinline__ v2u pack4(const f32x4 v) { v2u r; r.x = pk2(v[0], v[1]); r.y = pk2(v[2], v[3]); return r; }
; __device__ __forceinline__ f32x4 unpack4(const v2u w) { f32x4 r; r[0] = bflo(w.x); r[1] = bfhi(w.x); r[2] = bflo(w.y); r[3] = bfhi(w.y); return r; }
; __device__ __forceinline__ const char* upin(const char* p) { asm volatile("" : "+s"(p)); return p; }
; __device__ __forceinline__ char* upin(char* p) { asm volatile("" : "+s"(p)); return p; }
; template <bool GDN> __device__ __forceinline__ void scan_finish(const Frame& F, int b, int h, int dir, const ScanLane& L, int s, float* PEND, const f32x4 (&Oin)[4], const ScanFin& f) {
;     ...
;         f32x4 O[4]; float ss[4] = {0.f, 0.f, 0.f, 0.f};
; #pragma unroll
;         for (int t = 0; t < 4; ++t)
;             { const f32x4 pv = unpack4(f.pend[t]);
; #pragma unroll
;             for (int i = 0; i < 4; ++i) { O[t][i] = Oin[t][i] + pv[i]; ss[i] += O[t][i] * O[t][i]; } }
; #pragma unroll
;         for (int i = 0; i < 4; ++i) ss[i] = frsq(row16_sum(ss[i]) * (1.f / 64.f) + EPS);
;         char* mp = (char*)F.MIX + ((size_t)row0 * 1024 + (GDN ? 0 : 768) + h * 64) * 2;
; #pragma unroll
;         for (int i = 0; i < 4; ++i) { const f32x4 g = unpack4(f.gz[i]); f32x4 ov;
; #pragma unroll
;             for (int t = 0; t < 4; ++t) ov[t] = O[t][i] * ss[i] * g[t];
;             stu<v2u>(upin(mp + i * 2048), L.mix, pack4(ov)); }
	s_lshl_b32 s0, s1, 6
	s_cmp_lt_i32 s1, 4
	s_cselect_b32 s4, s63, s33
	s_add_i32 s4, s4, s0
	s_ashr_i32 s5, s4, 31
	s_lshl_b64 s[4:5], s[4:5], 11
	s_add_u32 s0, s26, s4
	s_addc_u32 s6, s27, s5
	s_add_u32 s4, s0, 0x600
	s_addc_u32 s5, s6, 0
	v_lshlrev_b32_e32 v246, 16, v12
	v_lshlrev_b32_e32 v247, 16, v14
	v_lshlrev_b32_e32 v220, 16, v16
	v_lshlrev_b32_e32 v221, 16, v18
	v_pk_add_f32 v[212:213], v[112:113], v[246:247]
	v_pk_add_f32 v[214:215], v[114:115], v[220:221]
	v_pk_mul_f32 v[204:205], v[212:213], v[212:213]
	v_pk_fma_f32 v[204:205], v[214:215], v[214:215], v[204:205]
	v_and_b32_e32 v246, 0xffff0000, v12
	v_and_b32_e32 v247, 0xffff0000, v14
	v_and_b32_e32 v220, 0xffff0000, v16
	v_and_b32_e32 v221, 0xffff0000, v18
	v_pk_add_f32 v[216:217], v[104:105], v[246:247]
	v_pk_add_f32 v[218:219], v[106:107], v[220:221]
	v_pk_mul_f32 v[206:207], v[216:217], v[216:217]
	v_pk_fma_f32 v[206:207], v[218:219], v[218:219], v[206:207]
	v_lshlrev_b32_e32 v246, 16, v13
	v_lshlrev_b32_e32 v247, 16, v15
	v_lshlrev_b32_e32 v220, 16, v17
	v_lshlrev_b32_e32 v221, 16, v19
	v_pk_add_f32 v[224:225], v[116:117], v[246:247]
	v_pk_add_f32 v[226:227], v[118:119], v[220:221]
	v_pk_mul_f32 v[208:209], v[224:225], v[224:225]
	v_pk_fma_f32 v[208:209], v[226:227], v[226:227], v[208:209]
	v_and_b32_e32 v246, 0xffff0000, v13
	v_and_b32_e32 v247, 0xffff0000, v15
	v_and_b32_e32 v220, 0xffff0000, v17
	v_and_b32_e32 v221, 0xffff0000, v19
	v_pk_add_f32 v[242:243], v[110:111], v[246:247]
	v_pk_add_f32 v[244:245], v[108:109], v[220:221]
	v_pk_mul_f32 v[210:211], v[242:243], v[242:243]
	v_pk_fma_f32 v[210:211], v[244:245], v[244:245], v[210:211]
	v_add_f32_e32 v204, v204, v205
	v_add_f32_e32 v206, v206, v207
	v_add_f32_e32 v208, v208, v209
	v_add_f32_e32 v210, v210, v211
	s_nop 0
	v_add_f32_dpp v204, v204, v204 quad_perm:[1,0,3,2] row_mask:0xf bank_mask:0xf bound_ctrl:1
	v_add_f32_dpp v206, v206, v206 quad_perm:[1,0,3,2] row_mask:0xf bank_mask:0xf bound_ctrl:1
	v_add_f32_dpp v208, v208, v208 quad_perm:[1,0,3,2] row_mask:0xf bank_mask:0xf bound_ctrl:1
	v_add_f32_dpp v210, v210, v210 quad_perm:[1,0,3,2] row_mask:0xf bank_mask:0xf bound_ctrl:1
	v_add_f32_dpp v204, v204, v204 quad_perm:[2,3,0,1] row_mask:0xf bank_mask:0xf bound_ctrl:1
	v_add_f32_dpp v206, v206, v206 quad_perm:[2,3,0,1] row_mask:0xf bank_mask:0xf bound_ctrl:1
	v_add_f32_dpp v208, v208, v208 quad_perm:[2,3,0,1] row_mask:0xf bank_mask:0xf bound_ctrl:1
	v_add_f32_dpp v210, v210, v210 quad_perm:[2,3,0,1] row_mask:0xf bank_mask:0xf bound_ctrl:1
	v_add_f32_dpp v204, v204, v204 row_half_mirror row_mask:0xf bank_mask:0xf bound_ctrl:1
	v_add_f32_dpp v206, v206, v206 row_half_mirror row_mask:0xf bank_mask:0xf bound_ctrl:1
	v_add_f32_dpp v208, v208, v208 row_half_mirror row_mask:0xf bank_mask:0xf bound_ctrl:1
	v_add_f32_dpp v210, v210, v210 row_half_mirror row_mask:0xf bank_mask:0xf bound_ctrl:1
	v_add_f32_dpp v204, v204, v204 row_mirror row_mask:0xf bank_mask:0xf bound_ctrl:1
	v_add_f32_dpp v206, v206, v206 row_mirror row_mask:0xf bank_mask:0xf bound_ctrl:1
	v_add_f32_dpp v208, v208, v208 row_mirror row_mask:0xf bank_mask:0xf bound_ctrl:1
	v_add_f32_dpp v210, v210, v210 row_mirror row_mask:0xf bank_mask:0xf bound_ctrl:1
	v_fmamk_f32 v204, v204, 0x3c800000, v231
	v_fmamk_f32 v206, v206, 0x3c800000, v231
	v_fmamk_f32 v208, v208, 0x3c800000, v231
	v_fmamk_f32 v210, v210, 0x3c800000, v231
	v_rsq_f32_e32 v204, v204
	v_rsq_f32_e32 v206, v206
	v_rsq_f32_e32 v208, v208
	v_rsq_f32_e32 v210, v210
	v_lshlrev_b32_e32 v246, 16, v130
	v_and_b32_e32 v247, 0xffff0000, v130
	v_lshlrev_b32_e32 v220, 16, v131
	v_and_b32_e32 v221, 0xffff0000, v131
	v_pk_mul_f32 v[212:213], v[212:213], v[204:205] op_sel_hi:[1,0]
	v_pk_mul_f32 v[214:215], v[214:215], v[204:205] op_sel_hi:[1,0]
	v_pk_mul_f32 v[212:213], v[212:213], v[246:247]
	v_pk_mul_f32 v[214:215], v[214:215], v[220:221]
	v_lshlrev_b32_e32 v246, 16, v132
	v_and_b32_e32 v247, 0xffff0000, v132
	v_lshlrev_b32_e32 v220, 16, v133
	v_and_b32_e32 v221, 0xffff0000, v133
	v_pk_mul_f32 v[216:217], v[216:217], v[206:207] op_sel_hi:[1,0]
	v_pk_mul_f32 v[218:219], v[218:219], v[206:207] op_sel_hi:[1,0]
	v_pk_mul_f32 v[216:217], v[216:217], v[246:247]
	v_pk_mul_f32 v[218:219], v[218:219], v[220:221]
	v_lshlrev_b32_e32 v246, 16, v134
	v_and_b32_e32 v247, 0xffff0000, v134
	v_lshlrev_b32_e32 v220, 16, v135
	v_and_b32_e32 v221, 0xffff0000, v135
	v_pk_mul_f32 v[224:225], v[224:225], v[208:209] op_sel_hi:[1,0]
	v_pk_mul_f32 v[226:227], v[226:227], v[208:209] op_sel_hi:[1,0]
	v_pk_mul_f32 v[224:225], v[224:225], v[246:247]
	v_pk_mul_f32 v[226:227], v[226:227], v[220:221]
	v_lshlrev_b32_e32 v246, 16, v136
	v_and_b32_e32 v247, 0xffff0000, v136
	v_lshlrev_b32_e32 v220, 16, v137
	v_and_b32_e32 v221, 0xffff0000, v137
	v_pk_mul_f32 v[242:243], v[242:243], v[210:211] op_sel_hi:[1,0]
	v_pk_mul_f32 v[244:245], v[244:245], v[210:211] op_sel_hi:[1,0]
	v_pk_mul_f32 v[242:243], v[242:243], v[246:247]
	v_pk_mul_f32 v[244:245], v[244:245], v[220:221]
	v_cvt_pk_bf16_f32 v204, v212, v213
	v_cvt_pk_bf16_f32 v205, v214, v215
	v_cvt_pk_bf16_f32 v210, v216, v217
	v_cvt_pk_bf16_f32 v211, v218, v219
	v_cvt_pk_bf16_f32 v206, v224, v225
	v_cvt_pk_bf16_f32 v207, v226, v227
	v_cvt_pk_bf16_f32 v218, v242, v243
	v_cvt_pk_bf16_f32 v219, v244, v245
	v_and_b32_e32 v220, 1, v232
	v_mul_u32_u24_e32 v220, 0x7f8, v220
	v_add_u32_e32 v220, v153, v220
	s_mov_b32 vcc_lo, 0x55555555
	s_mov_b32 vcc_hi, 0x55555555
	v_cndmask_b32_dpp v208, v210, v204, vcc quad_perm:[1,0,3,2] row_mask:0xf bank_mask:0xf
	v_cndmask_b32_dpp v209, v211, v205, vcc quad_perm:[1,0,3,2] row_mask:0xf bank_mask:0xf
	v_cndmask_b32_dpp v216, v218, v206, vcc quad_perm:[1,0,3,2] row_mask:0xf bank_mask:0xf
	v_cndmask_b32_dpp v217, v219, v207, vcc quad_perm:[1,0,3,2] row_mask:0xf bank_mask:0xf
	s_not_b64 vcc, vcc
	v_cndmask_b32_dpp v210, v204, v210, vcc quad_perm:[1,0,3,2] row_mask:0xf bank_mask:0xf
	v_cndmask_b32_dpp v211, v205, v211, vcc quad_perm:[1,0,3,2] row_mask:0xf bank_mask:0xf
	v_cndmask_b32_dpp v218, v206, v218, vcc quad_perm:[1,0,3,2] row_mask:0xf bank_mask:0xf
	v_cndmask_b32_dpp v219, v207, v219, vcc quad_perm:[1,0,3,2] row_mask:0xf bank_mask:0xf
	global_store_dwordx4 v220, v[208:211], s[4:5]
	s_add_u32 s4, s0, 0xe00
	s_addc_u32 s5, s6, 0
	s_add_u32 s4, s0, 0x1600
	s_addc_u32 s5, s6, 0
	global_store_dwordx4 v220, v[216:219], s[4:5]
	s_add_u32 s4, s0, 0x1e00
	s_addc_u32 s5, s6, 0
	s_cbranch_execz .LBB0_454

; template <bool GDN, int NT> __device__ __forceinline__ void scan_load(const Frame& F, int b, int h, int dir, const ScanLane& L, int s, ScanOps<NT>& o) {
;     ...
;         const char* zq = upin((const char*)F.Z + ((size_t)chunk_row0(b, cidx) * ZW + ZC_LQ + h * 64) * 2);
; #pragma unroll
;         for (int ks = 0; ks < 2; ++ks) { o.Qf[ks] = ldu<bf16x8>(zq + ks * 64, L.zq); o.Mf[ks] = o.Qf[ks]; }
;         const char* base = (const char*)F.PM + (size_t)ud * 20480;
;         const char* bO = upin(base); const char* bB = upin(base + 10240);
; #pragma unroll
;         for (int pr = 0; pr < 2; ++pr) { const v4u qb = ldun<v4u>(bB + pr * 1024, L.o16p), qo = ldun<v4u>(bO + pr * 1024, L.o16p);
;             o.bv[2 * pr] = (v2u){qb.x, qb.y}; o.bv[2 * pr + 1] = (v2u){qb.z, qb.w}; o.ov[2 * pr] = (v2u){qo.x, qo.y}; o.ov[2 * pr + 1] = (v2u){qo.z, qo.w}; }
;         o.bv[4] = ldun<v2u>(bB + 2048, L.o8); o.ov[4] = ldun<v2u>(bO + 2048, L.o8);
;         o.wi = ldu<f32x4>(upin((const char*)F.WI + (size_t)ud * 256), L.wi);
;     ...
;     const float gl = ((const LAS float*)(St + 4 * 80 * 72))[(dir ? (s < 4 ? 3 - s : 39 - s) : s) * 2 + dir];
;     f32x4 O[NT];
; #pragma unroll
;     for (int t = 0; t < NT; ++t) {
;         const LAS bf16_t* sp2 = Sb + (16 * t + lr) * 72 + 8 * lq;
;         const bf16x8 s0 = *(const LAS bf16x8*)sp2, s1 = *(const LAS bf16x8*)(sp2 + 32);
;         const f32x4 bv = unpack4(use.bv[t]), ov = unpack4(use.ov[t]);
;         if (GDN) {
;             f32x4 o = ov, sn = S[t] * gl + bv;
;             o = __builtin_amdgcn_mfma_f32_16x16x32_bf16(use.Qf[0], s0, o, 0, 0, 0); o = __builtin_amdgcn_mfma_f32_16x16x32_bf16(use.Qf[1], s1, o, 0, 0, 0);
;             sn = __builtin_amdgcn_mfma_f32_16x16x32_bf16(use.Mf[0], s0, sn, 0, 0, 0); sn = __builtin_amdgcn_mfma_f32_16x16x32_bf16(use.Mf[1], s1, sn, 0, 0, 0);
;             S[t] = sn; O[t] = o;
;         } else {
;             f32x4 o = {0.f, 0.f, 0.f, 0.f};
;             o = __builtin_amdgcn_mfma_f32_16x16x32_bf16(use.Qf[0], s0, o, 0, 0, 0); o = __builtin_amdgcn_mfma_f32_16x16x32_bf16(use.Qf[1], s1, o, 0, 0, 0);
;             S[t] = S[t] * gl + bv; O[t] = o * use.wi + ov; }
;     }
;     if (!GDN) {
; #pragma unroll
;         for (int i = 0; i < 4; ++i) { const float den = row16_bcast<0>(O[NT - 1][i]), fl = row16_bcast<1>(O[NT - 1][i]); const float dv = frcp(fmaxf(fabsf(den), fl));
; #pragma unroll
.LBB0_446:
	s_min_u32 s0, s3, 33
	s_add_i32 s4, s0, 2
	s_sub_i32 s5, 37, s0
	s_and_b64 s[0:1], s[90:91], exec
	s_cselect_b32 s0, s4, s5
	s_lshl_b32 s1, s0, 6
	s_add_i32 s1, s1, s33
	s_add_i32 s0, s0, s31
	s_lshl_b32 s0, s0, 1
	s_mulk_i32 s1, 0xd00
	s_add_i32 s92, s0, s68
	s_or_b32 s0, s36, s1
	s_mov_b32 s1, s37
	s_lshl_b64 s[0:1], s[0:1], 1
	s_add_u32 s0, s16, s0
	s_addc_u32 s1, s17, s1
	global_load_dwordx4 v[40:43], v150, s[0:1]
	global_load_dwordx4 v[36:39], v150, s[0:1] offset:64
	s_mul_i32 s0, s92, 0x5000
	v_readlane_b32 s4, v254, 46
	s_mul_hi_u32 s1, s92, 0x5000
	s_add_u32 s0, s4, s0
	v_readlane_b32 s4, v254, 47
	s_addc_u32 s1, s4, s1
	s_mov_b64 s[4:5], s[0:1]
	s_add_u32 s0, s0, 0x2800
	s_addc_u32 s1, s1, 0
	global_load_dwordx4 v[92:95], v149, s[0:1] nt
	global_load_dwordx4 v[64:67], v149, s[0:1] offset:1024 nt
	global_load_dwordx4 v[96:99], v149, s[4:5] nt
	global_load_dwordx4 v[68:71], v149, s[4:5] offset:1024 nt
	global_load_dwordx2 v[146:147], v148, s[0:1] offset:2048 nt
	global_load_dwordx2 v[142:143], v148, s[4:5] offset:2048 nt
	s_lshl_b64 s[0:1], s[92:93], 8
	v_readlane_b32 s4, v254, 52
	v_readlane_b32 s5, v254, 53
	s_add_u32 s0, s4, s0
	s_addc_u32 s1, s5, s1
	s_add_i32 s4, s24, 38
	global_load_dwordx4 v[60:63], v0, s[0:1]
	s_and_b64 s[0:1], s[90:91], exec
	s_cselect_b32 s0, s3, s4
	s_lshl_b32 s0, s0, 3
	s_add_i32 s0, s34, s0
	v_mov_b32_e32 v0, s0
	ds_read_b32 v0, v0 offset:46080
	ds_read_b128 v[104:107], v203
	ds_read_b128 v[108:111], v203 offset:64
	ds_read_b128 v[212:215], v203 offset:2304
	ds_read_b128 v[216:219], v203 offset:2368
	ds_read_b128 v[224:227], v203 offset:4608
	ds_read_b128 v[242:245], v203 offset:4672
	s_waitcnt lgkmcnt(5)
	v_mfma_f32_16x16x32_bf16 v[104:107], v[24:27], v[104:107], 0
	v_lshlrev_b32_e32 v112, 16, v44
	v_and_b32_e32 v113, 0xffff0000, v44
	v_lshlrev_b32_e32 v114, 16, v52
	s_waitcnt lgkmcnt(4)
	v_mfma_f32_16x16x32_bf16 v[104:107], v[20:23], v[108:111], v[104:107]
	v_and_b32_e32 v115, 0xffff0000, v52
	v_lshlrev_b32_e32 v52, 16, v53
	v_and_b32_e32 v53, 0xffff0000, v53
	v_pk_fma_f32 v[190:191], v[190:191], v[0:1], v[112:113] op_sel_hi:[1,0,1]
	v_lshlrev_b32_e32 v44, 16, v45
	s_nop 2
	v_pk_fma_f32 v[112:113], v[100:101], v[104:105], v[114:115]
	v_pk_fma_f32 v[114:115], v[102:103], v[106:107], v[52:53]
	v_and_b32_e32 v45, 0xffff0000, v45
	v_pk_fma_f32 v[192:193], v[192:193], v[0:1], v[44:45] op_sel_hi:[1,0,1]
	v_lshlrev_b32_e32 v52, 16, v46
	v_and_b32_e32 v53, 0xffff0000, v46
	v_lshlrev_b32_e32 v116, 16, v47
	v_and_b32_e32 v117, 0xffff0000, v47
	s_waitcnt lgkmcnt(3)
	v_mfma_f32_16x16x32_bf16 v[44:47], v[24:27], v[212:215], 0
	v_lshlrev_b32_e32 v118, 16, v54
	v_and_b32_e32 v119, 0xffff0000, v54
	v_lshlrev_b32_e32 v54, 16, v55
	s_waitcnt lgkmcnt(2)
	v_mfma_f32_16x16x32_bf16 v[44:47], v[20:23], v[216:219], v[44:47]
	ds_read_b128 v[212:215], v203 offset:6912
	ds_read_b128 v[216:219], v203 offset:6976
	v_and_b32_e32 v55, 0xffff0000, v55
	v_pk_fma_f32 v[154:155], v[154:155], v[0:1], v[52:53] op_sel_hi:[1,0,1]
	v_lshlrev_b32_e32 v108, 16, v28
	v_and_b32_e32 v109, 0xffff0000, v28
	v_lshlrev_b32_e32 v110, 16, v32
	s_nop 2
	v_pk_fma_f32 v[104:105], v[100:101], v[44:45], v[118:119]
	v_pk_fma_f32 v[106:107], v[102:103], v[46:47], v[54:55]
	s_waitcnt lgkmcnt(3)
	v_mfma_f32_16x16x32_bf16 v[44:47], v[24:27], v[224:227], 0
	v_and_b32_e32 v111, 0xffff0000, v32
	v_lshlrev_b32_e32 v32, 16, v33
	v_and_b32_e32 v33, 0xffff0000, v33
	s_waitcnt lgkmcnt(2)
	v_mfma_f32_16x16x32_bf16 v[44:47], v[20:23], v[242:245], v[44:47]
	ds_read_b128 v[224:227], v203 offset:9216
	ds_read_b128 v[242:245], v203 offset:9280
	v_fma_f32 v188, v188, v0, v116
	v_fma_f32 v189, v189, v0, v117
	v_pk_fma_f32 v[182:183], v[182:183], v[0:1], v[108:109] op_sel_hi:[1,0,1]
	v_lshlrev_b32_e32 v28, 16, v29
	v_and_b32_e32 v29, 0xffff0000, v29
	v_pk_fma_f32 v[186:187], v[186:187], v[0:1], v[28:29] op_sel_hi:[1,0,1]
	s_nop 1
	v_pk_fma_f32 v[108:109], v[100:101], v[44:45], v[110:111]
	v_pk_fma_f32 v[116:117], v[102:103], v[46:47], v[32:33]
	v_lshlrev_b32_e32 v32, 16, v30
	v_and_b32_e32 v33, 0xffff0000, v30
	v_lshlrev_b32_e32 v110, 16, v31
	v_and_b32_e32 v111, 0xffff0000, v31
	s_waitcnt lgkmcnt(3)
	v_mfma_f32_16x16x32_bf16 v[28:31], v[24:27], v[212:215], 0
	v_lshlrev_b32_e32 v118, 16, v34
	v_and_b32_e32 v119, 0xffff0000, v34
	v_lshlrev_b32_e32 v34, 16, v35
	s_waitcnt lgkmcnt(2)
	v_mfma_f32_16x16x32_bf16 v[28:31], v[20:23], v[216:219], v[28:31]
	v_and_b32_e32 v35, 0xffff0000, v35
	v_pk_fma_f32 v[178:179], v[178:179], v[0:1], v[32:33] op_sel_hi:[1,0,1]
	v_pk_fma_f32 v[162:163], v[162:163], v[0:1], v[110:111] op_sel_hi:[1,0,1]
	v_lshlrev_b32_e32 v110, 16, v138
	v_and_b32_e32 v111, 0xffff0000, v138
	s_nop 2
	v_pk_fma_f32 v[44:45], v[100:101], v[28:29], v[118:119]
	v_pk_fma_f32 v[46:47], v[102:103], v[30:31], v[34:35]
	s_waitcnt lgkmcnt(1)
	v_mfma_f32_16x16x32_bf16 v[24:27], v[24:27], v[224:227], 0
	v_lshlrev_b32_e32 v28, 16, v139
	v_and_b32_e32 v29, 0xffff0000, v139
	v_lshlrev_b32_e32 v52, 16, v140
	s_waitcnt lgkmcnt(0)
	v_mfma_f32_16x16x32_bf16 v[20:23], v[20:23], v[242:245], v[24:27]
	v_and_b32_e32 v53, 0xffff0000, v140
	v_lshlrev_b32_e32 v54, 16, v141
	v_and_b32_e32 v55, 0xffff0000, v141
	v_pk_fma_f32 v[164:165], v[164:165], v[0:1], v[54:55] op_sel_hi:[1,0,1]
	v_pk_fma_f32 v[180:181], v[180:181], v[0:1], v[52:53] op_sel_hi:[1,0,1]
	s_nop 2
	v_pk_fma_f32 v[20:21], v[100:101], v[20:21], v[110:111]
	v_pk_fma_f32 v[22:23], v[102:103], v[22:23], v[28:29]
	s_nop 0
	v_mov_b32_dpp v24, v20 row_newbcast:1 row_mask:0xf bank_mask:0xf bound_ctrl:1
	v_max_f32_dpp v20, |v20|, v24 row_newbcast:0 row_mask:0xf bank_mask:0xf bound_ctrl:1
	v_rcp_f32_e32 v28, v20
	s_nop 0
	v_mov_b32_dpp v20, v21 row_newbcast:1 row_mask:0xf bank_mask:0xf bound_ctrl:1
	v_max_f32_dpp v20, |v21|, v20 row_newbcast:0 row_mask:0xf bank_mask:0xf bound_ctrl:1
	v_mov_b32_dpp v21, v22 row_newbcast:1 row_mask:0xf bank_mask:0xf bound_ctrl:1
	v_max_f32_dpp v21, |v22|, v21 row_newbcast:0 row_mask:0xf bank_mask:0xf bound_ctrl:1
	v_rcp_f32_e32 v30, v21
	v_mov_b32_dpp v22, v23 row_newbcast:1 row_mask:0xf bank_mask:0xf bound_ctrl:1
	v_mov_b32_dpp v21, v23 row_newbcast:0 row_mask:0xf bank_mask:0xf bound_ctrl:1
	v_max_f32_e64 v21, |v21|, v22
	v_rcp_f32_e32 v31, v21
	v_rcp_f32_e32 v29, v20
	v_pk_mul_f32 v[20:21], v[114:115], v[30:31]
	v_pk_mul_f32 v[24:25], v[112:113], v[28:29]
	v_pk_mul_f32 v[110:111], v[106:107], v[30:31]
	v_pk_mul_f32 v[104:105], v[104:105], v[28:29]
	v_pk_mul_f32 v[22:23], v[116:117], v[30:31]
	v_pk_mul_f32 v[26:27], v[108:109], v[28:29]
	v_pk_mul_f32 v[108:109], v[46:47], v[30:31]
	v_pk_mul_f32 v[106:107], v[44:45], v[28:29]
	s_branch .LBB0_456
